# gdn_prep: counted vmcnt(8) at the top of an item instead of vmcnt(0) (first item drained before the loop)
# speedup vs baseline: 1.0046x; 1.0046x over previous
; #define LAS __attribute__((address_space(3)))
; __device__ __forceinline__ void gdn_prep_all(const Params& P, LAS unsigned char* lds, int tid, int lane, int wave, int G) {
;     const int hh = wave >> 2, tih = tid & 255, wq = wave & 3;
;     LAS unsigned char* hb = lds + hh * HEAD_LDS;
;     LAS float* const scb0 = (LAS float*)(hb + SC_OFF); LAS float* const scb1 = (LAS float*)(hb + SC2_OFF);
;     int par = 0;
;     const float* Gd = (const float*)(P.ws + WS_G); const float* Bd = (const float*)(P.ws + WS_BETA); float* GT = (float*)(P.ws + WS_GT);
;     const bf16* QKVA = (const bf16*)(P.ws + WS_QKVA);
;     const int t1 = tih >> 2, cg = tih & 3;
;     v4u pre[7]; float gpre = 0.f, bpre = 0.f;
;     int cw_hp = -1;
;     const f32x4 z4 = {0.f, 0.f, 0.f, 0.f};
;     ...
;     if ((int)blockIdx.x < NCU * 4) { GDN_PREFETCH((int)blockIdx.x); if (wq == 0) GDN_GATES(scb0, (int)blockIdx.x); }
; #pragma unroll 1
;     for (int item = blockIdx.x; item < NCU * 4; item += G) {
;         const GdnItem I = gdn_item(item); const int hp = item & 3, h = 2 * hp + hh;
;         LAS float* const sc = par ? scb1 : scb0;
;         if (hp != cw_hp) {
.LBB0_344:
	s_andn2_b64 vcc, exec, s[0:1]
	s_cbranch_vccnz .LBB0_472
	s_add_i32 s83, s2, 0xd400
	s_add_i32 s4, s2, 0xf500
	s_lshl_b32 s11, s81, 4
	s_cmp_gt_u32 s81, 1
	s_cselect_b64 s[22:23], -1, 0
	s_cmp_lt_u32 s81, 2
	v_and_b32_e32 v110, 15, v149
	s_cselect_b64 s[0:1], -1, 0
	s_movk_i32 s10, 0x4800
	s_and_b64 s[8:9], s[0:1], exec
	v_cmp_eq_u32_e32 vcc, 0, v110
	s_cselect_b32 s8, s10, 0x2400
	s_cselect_b32 s10, 64, 0x100
	v_cndmask_b32_e64 v121, 0, 1.0, vcc
	v_cmp_eq_u32_e32 vcc, 1, v110
	s_add_i32 s14, s2, s8
	s_lshl_b32 s8, s33, 5
	v_cndmask_b32_e64 v122, 0, 1.0, vcc
	v_cmp_eq_u32_e32 vcc, 2, v110
	s_cmp_lg_u32 s81, 0
	s_cselect_b64 s[12:13], -1, 0
	v_cndmask_b32_e64 v123, 0, 1.0, vcc
	v_cmp_eq_u32_e32 vcc, 3, v110
	s_cmp_lg_u32 s81, 3
	v_and_or_b32 v48, s8, 32, v110
	v_cndmask_b32_e64 v124, 0, 1.0, vcc
	v_cmp_eq_u32_e32 vcc, 4, v110
	s_cselect_b64 s[8:9], -1, 0
	v_lshlrev_b32_e32 v53, 4, v30
	v_cndmask_b32_e64 v125, 0, 1.0, vcc
	v_cmp_eq_u32_e32 vcc, 5, v110
	v_cndmask_b32_e64 v30, 0, 1, s[12:13]
	s_and_b64 s[12:13], s[8:9], exec
	v_cndmask_b32_e64 v126, 0, 1.0, vcc
	v_cmp_eq_u32_e32 vcc, 6, v110
	v_readfirstlane_b32 s12, v30
	s_cselect_b32 s12, s12, 2
	v_cndmask_b32_e64 v127, 0, 1.0, vcc
	v_cmp_eq_u32_e32 vcc, 7, v110
	s_add_i32 s13, s12, 1
	v_lshrrev_b32_e32 v39, 4, v1
	v_cndmask_b32_e64 v128, 0, 1.0, vcc
	v_cmp_eq_u32_e32 vcc, 8, v110
	s_mul_i32 s13, s13, s12
	v_lshlrev_b32_e32 v111, 2, v39
	v_cndmask_b32_e64 v129, 0, 1.0, vcc
	v_cmp_eq_u32_e32 vcc, 9, v110
	s_lshr_b32 s13, s13, 1
	s_lshl_b32 s12, s12, 4
	v_cndmask_b32_e64 v130, 0, 1.0, vcc
	v_cmp_eq_u32_e32 vcc, 10, v110
	v_lshlrev_b32_e32 v48, 1, v48
	s_sub_i32 s13, s81, s13
	v_cndmask_b32_e64 v131, 0, 1.0, vcc
	v_cmp_eq_u32_e32 vcc, 11, v110
	v_or_b32_e32 v30, s12, v110
	v_or_b32_e32 v116, s12, v111
	v_cndmask_b32_e64 v132, 0, 1.0, vcc
	v_cmp_eq_u32_e32 vcc, 12, v110
	v_add_u32_e32 v137, s14, v48
	v_add_u32_e32 v139, s2, v48
	v_mbcnt_lo_u32_b32 v48, -1, 0
	v_mul_u32_u24_e32 v56, 0x90, v30
	v_lshl_or_b32 v115, s13, 4, v110
	v_or_b32_e32 v30, 1, v116
	v_cndmask_b32_e64 v133, 0, 1.0, vcc
	v_cmp_eq_u32_e32 vcc, 13, v110
	v_mbcnt_hi_u32_b32 v48, -1, v48
	v_lshlrev_b32_e32 v50, 3, v1
	v_cmp_gt_i32_e64 s[30:31], v115, v30
	v_or_b32_e32 v30, 2, v116
	v_cndmask_b32_e64 v134, 0, 1.0, vcc
	v_cmp_eq_u32_e32 vcc, 14, v110
	v_and_b32_e32 v147, 64, v48
	v_cmp_lt_i32_e64 s[16:17], v115, v30
	s_or_b32 s13, s81, 4
	v_cndmask_b32_e64 v135, 0, 1.0, vcc
	v_cmp_eq_u32_e32 vcc, 15, v110
	v_lshl_or_b32 v96, s81, 12, v50
	v_xor_b32_e32 v50, 1, v48
	v_add_u32_e32 v141, 64, v147
	v_writelane_b32 v247, s16, 33
	s_cmp_gt_u32 s13, 5
	v_cndmask_b32_e64 v136, 0, 1.0, vcc
	v_cmp_lt_i32_e32 vcc, v50, v141
	v_writelane_b32 v247, s17, 34
	v_cmp_gt_i32_e64 s[16:17], v115, v30
	s_cselect_b32 s15, 3, 2
	v_cndmask_b32_e32 v50, v48, v50, vcc
	v_writelane_b32 v247, s16, 35
	v_or_b32_e32 v30, 3, v116
	s_add_i32 s18, s15, 1
	v_lshlrev_b32_e32 v140, 2, v50
	v_xor_b32_e32 v50, 2, v48
	v_writelane_b32 v247, s17, 36
	v_cmp_lt_i32_e64 s[16:17], v115, v30
	s_mul_i32 s18, s18, s15
	v_cmp_lt_i32_e32 vcc, v50, v141
	v_writelane_b32 v247, s16, 37
	s_lshr_b32 s18, s18, 1
	v_cndmask_b32_e32 v50, v48, v50, vcc
	v_writelane_b32 v247, s17, 38
	v_cmp_gt_i32_e64 s[16:17], v115, v30
	s_sub_i32 s13, s13, s18
	s_lshl_b32 s15, s15, 4
	v_lshlrev_b32_e32 v141, 2, v50
	v_add_u32_e32 v50, -1, v48
	v_writelane_b32 v247, s16, 39
	v_lshl_or_b32 v117, s13, 4, v110
	v_or_b32_e32 v118, s15, v111
	v_cmp_lt_i32_e32 vcc, v50, v147
	v_writelane_b32 v247, s17, 40
	v_cmp_lt_i32_e64 s[16:17], v117, v118
	s_or_b32 s13, s81, 8
	v_cndmask_b32_e32 v50, v50, v48, vcc
	v_writelane_b32 v247, s16, 41
	s_cmp_lt_u32 s13, 10
	v_lshlrev_b32_e32 v142, 2, v50
	v_add_u32_e32 v50, -2, v48
	v_or_b32_e32 v43, s11, v111
	v_or_b32_e32 v114, s11, v110
	v_writelane_b32 v247, s17, 42
	v_cmp_gt_i32_e64 s[16:17], v117, v118
	s_cselect_b64 s[52:53], -1, 0
	s_add_i32 s11, s11, 32
	v_cmp_lt_i32_e32 vcc, v50, v147
	v_writelane_b32 v247, s16, 43
	v_or_b32_e32 v69, s11, v110
	v_or_b32_e32 v71, 48, v111
	v_cndmask_b32_e32 v50, v50, v48, vcc
	v_writelane_b32 v247, s17, 44
	v_cmp_lt_u32_e64 s[16:17], v69, v71
	v_lshlrev_b32_e32 v143, 2, v50
	v_add_u32_e32 v50, -4, v48
	v_writelane_b32 v247, s16, 31
	v_cmp_lt_i32_e32 vcc, v50, v147
	v_mul_u32_u24_e32 v74, 0x110, v71
	v_writelane_b32 v247, s17, 32
	v_cmp_gt_u32_e64 s[16:17], v69, v71
	v_cndmask_b32_e32 v50, v50, v48, vcc
	v_mul_u32_u24_e32 v119, 0x90, v71
	v_writelane_b32 v247, s16, 45
	v_or_b32_e32 v71, 49, v111
	v_lshlrev_b32_e32 v144, 2, v50
	v_add_u32_e32 v50, -8, v48
	v_writelane_b32 v247, s17, 46
	v_cmp_lt_u32_e64 s[16:17], v69, v71
	v_cmp_lt_i32_e32 vcc, v50, v147
	v_writelane_b32 v246, s64, 2
	v_writelane_b32 v247, s16, 29
	v_cndmask_b32_e32 v50, v50, v48, vcc
	v_writelane_b32 v246, s65, 3
; #define LAS __attribute__((address_space(3)))
; __device__ __forceinline__ void gdn_prep_all(const Params& P, LAS unsigned char* lds, int tid, int lane, int wave, int G) {
;     const int hh = wave >> 2, tih = tid & 255, wq = wave & 3;
;     LAS unsigned char* hb = lds + hh * HEAD_LDS;
;     LAS float* const scb0 = (LAS float*)(hb + SC_OFF); LAS float* const scb1 = (LAS float*)(hb + SC2_OFF);
;     int par = 0;
;     const float* Gd = (const float*)(P.ws + WS_G); const float* Bd = (const float*)(P.ws + WS_BETA); float* GT = (float*)(P.ws + WS_GT);
;     const bf16* QKVA = (const bf16*)(P.ws + WS_QKVA);
;     const int t1 = tih >> 2, cg = tih & 3;
;     v4u pre[7]; float gpre = 0.f, bpre = 0.f;
;     int cw_hp = -1;
;     const f32x4 z4 = {0.f, 0.f, 0.f, 0.f};
;     ...
;     if ((int)blockIdx.x < NCU * 4) { GDN_PREFETCH((int)blockIdx.x); if (wq == 0) GDN_GATES(scb0, (int)blockIdx.x); }
; #pragma unroll 1
;     for (int item = blockIdx.x; item < NCU * 4; item += G) {
;         const GdnItem I = gdn_item(item); const int hp = item & 3, h = 2 * hp + hh;
;         LAS float* const sc = par ? scb1 : scb0;
;         if (hp != cw_hp) {
	v_writelane_b32 v247, s17, 30
	v_cmp_gt_u32_e64 s[16:17], v69, v71
	v_lshlrev_b32_e32 v145, 2, v50
	v_add_u32_e32 v50, -16, v48
	v_writelane_b32 v246, s16, 4
	v_or_b32_e32 v71, 50, v111
	v_cmp_lt_i32_e32 vcc, v50, v147
	v_writelane_b32 v246, s17, 5
	v_cmp_lt_u32_e64 s[16:17], v69, v71
	v_cndmask_b32_e32 v50, v50, v48, vcc
	v_lshlrev_b32_e32 v146, 2, v50
	v_writelane_b32 v246, s16, 6
	v_subrev_u32_e32 v50, 32, v48
	v_or_b32_e32 v30, s15, v110
	v_writelane_b32 v246, s17, 7
	v_cmp_gt_u32_e64 s[16:17], v69, v71
	v_cmp_lt_i32_e32 vcc, v50, v147
	v_mul_u32_u24_e32 v62, 0x90, v30
	v_or_b32_e32 v30, 1, v118
	v_writelane_b32 v246, s16, 8
	v_or_b32_e32 v71, 51, v111
	v_cndmask_b32_e32 v50, v50, v48, vcc
	v_cmp_gt_i32_e64 s[40:41], v117, v30
	v_or_b32_e32 v30, 2, v118
	v_writelane_b32 v246, s17, 9
	v_cmp_lt_u32_e64 s[16:17], v69, v71
	v_or_b32_e32 v77, 2, v111
	v_lshlrev_b32_e32 v147, 2, v50
	v_bfrev_b32_e32 v50, 0.5
	v_lshlrev_b32_e32 v44, 1, v110
	v_cmp_lt_i32_e64 s[42:43], v117, v30
	v_cmp_gt_i32_e64 s[44:45], v117, v30
	v_or_b32_e32 v30, 3, v118
	v_writelane_b32 v246, s16, 10
	v_mul_u32_u24_e32 v120, 0x240, v39
	v_mul_u32_u24_e32 v138, 0x90, v77
	v_lshl_or_b32 v148, v48, 2, v50
	v_lshl_add_u32 v48, v78, 2, s2
	v_lshrrev_b32_e32 v109, 2, v78
	v_and_b32_e32 v31, 3, v149
	s_movk_i32 s5, 0x90
	v_mov_b32_e32 v35, s2
	v_and_b32_e32 v41, 48, v149
	v_add_u32_e32 v112, s2, v44
	s_movk_i32 s12, 0x110
	v_cmp_lt_i32_e64 s[46:47], v117, v30
	v_cmp_gt_i32_e64 s[48:49], v117, v30
	v_or_b32_e32 v30, 48, v1
	v_writelane_b32 v246, s17, 11
	v_cmp_gt_u32_e64 s[16:17], v69, v71
	v_or_b32_e32 v71, 15, v1
	v_add_u32_e32 v151, 0xe900, v48
	v_or_b32_e32 v48, v138, v44
	v_or_b32_e32 v44, v120, v44
	v_lshlrev_b32_e32 v33, 6, v31
	v_mad_u32_u24 v37, v109, s5, v35
	v_lshlrev_b32_e32 v31, 5, v31
	v_lshlrev_b32_e32 v45, 3, v39
	v_lshlrev_b32_e32 v46, 2, v110
	v_mad_u32_u24 v51, v114, s5, v35
	v_mad_u32_u24 v39, v41, s12, v35
	v_mad_u32_u24 v75, v71, s12, v35
	v_mad_u32_u24 v77, v110, s12, v35
	v_mad_u32_u24 v35, v30, s12, v35
	v_readlane_b32 s12, v247, 0
	v_add_u32_e32 v44, 0, v44
	v_add_u32_e32 v42, s2, v41
	v_lshlrev_b32_e32 v113, 4, v1
	v_add_u32_e32 v47, s2, v46
	v_lshl_add_u32 v49, v110, 6, s2
	v_lshlrev_b32_e32 v52, 4, v78
	v_lshlrev_b32_e32 v32, 4, v32
	v_lshlrev_b32_e32 v34, 4, v34
	v_lshlrev_b32_e32 v36, 4, v36
	v_lshlrev_b32_e32 v38, 4, v38
	v_lshlrev_b32_e32 v40, 4, v40
	v_add_u32_e32 v54, s2, v31
	v_mul_u32_u24_e32 v55, 0x180, v109
	v_mul_lo_u32 v57, v115, s5
	v_lshl_add_u32 v58, v115, 2, s2
	v_lshl_add_u32 v59, v115, 1, s2
	v_mul_u32_u24_e32 v60, 0x110, v116
	v_mul_u32_u24_e32 v61, 0x90, v116
	v_mul_lo_u32 v63, v117, s5
	v_lshl_add_u32 v64, v117, 2, s2
	v_lshl_add_u32 v65, v117, 1, s2
	v_mul_u32_u24_e32 v66, 0x110, v118
	v_mul_u32_u24_e32 v67, 0x90, v118
	v_mul_u32_u24_e32 v68, 0x90, v30
	v_mul_u32_u24_e32 v70, 0x90, v69
	v_lshl_add_u32 v72, v69, 2, s2
	v_lshl_add_u32 v73, v69, 1, s2
	v_mul_u32_u24_e32 v43, 0x90, v43
	v_lshlrev_b32_e32 v69, 2, v41
	v_lshlrev_b32_e32 v76, 6, v41
	v_lshlrev_b32_e32 v71, 6, v71
	v_mov_b32_e32 v30, 0
	v_readlane_b32 s13, v247, 1
	s_add_u32 s85, s12, 0x23900000
	v_add_u32_e32 v48, 0, v48
	v_add_u32_e32 v154, 0x2400, v44
	v_mul_u32_u24_e32 v44, 0x90, v110
	s_mov_b32 s84, 0
	v_cmp_lt_i32_e64 s[24:25], v115, v116
	v_cmp_gt_i32_e64 s[26:27], v115, v116
	v_cmp_le_i32_e64 s[28:29], v115, v116
	v_cmp_le_i32_e64 s[38:39], v117, v118
	v_writelane_b32 v246, s16, 12
	v_mov_b32_e32 v97, v30
	v_lshl_or_b32 v98, s81, 11, v113
	v_mov_b32_e32 v99, v30
	s_addc_u32 s86, s13, 0
	s_mov_b32 s87, -1
	v_add_u32_e32 v150, s2, v45
	v_add_u32_e32 v152, 0x2400, v48
	v_or_b32_e32 v153, 0x200, v46
	v_add3_u32 v155, v44, v45, 0
	v_add_u32_e32 v156, s2, v52
	v_add_u32_e32 v157, s2, v53
	v_add_u32_e32 v158, s2, v32
	v_add_u32_e32 v159, s2, v34
	v_add_u32_e32 v160, s2, v36
	v_add_u32_e32 v161, s2, v38
	v_add_u32_e32 v162, s2, v40
	v_add_u32_e32 v163, v54, v55
	v_add_u32_e32 v164, s2, v33
	v_add_u32_e32 v165, v37, v31
	s_movk_i32 s97, 0xc00
	v_add_u32_e32 v166, v42, v56
	v_add_u32_e32 v167, v42, v57
	v_add_u32_e32 v168, v42, v62
	v_add_u32_e32 v169, v42, v63
	v_add_u32_e32 v170, v42, v68
	v_add_u32_e32 v171, v42, v70
	v_add_u32_e32 v172, v39, v69
	v_add_u32_e32 v173, v75, v69
	v_add_u32_e32 v174, v47, v76
	v_add_u32_e32 v175, v47, v71
	s_lshl_b32 s36, s10, 2
	v_add_u32_e32 v176, v49, v41
	v_add_u32_e32 v177, v77, v41
	s_mov_b32 s10, 0x80008000
	v_add_u32_e32 v178, v35, v41
	v_add_u32_e32 v179, v51, v45
	v_add_u32_e32 v180, v58, v60
	v_add_u32_e32 v181, v59, v61
	v_add_u32_e32 v182, v64, v66
	v_add_u32_e32 v183, v65, v67
	v_add_u32_e32 v184, v72, v74
	v_add_u32_e32 v185, v73, v119
	v_add_u32_e32 v186, v112, v43
	s_mov_b32 s2, s96
	v_writelane_b32 v246, s17, 13
	s_waitcnt vmcnt(0)
	s_branch .LBB0_347

; #define LAS __attribute__((address_space(3)))
; __device__ __forceinline__ void unpack8(v4u w, float (&f)[8]) { f[0] = bflo(w.x); f[1] = bfhi(w.x); f[2] = bflo(w.y); f[3] = bfhi(w.y); f[4] = bflo(w.z); f[5] = bfhi(w.z); f[6] = bflo(w.w); f[7] = bfhi(w.w); }
; __device__ __forceinline__ void gdn_prep_all(const Params& P, LAS unsigned char* lds, int tid, int lane, int wave, int G) {
;     ...
;         for (int k = 0; k < 7; ++k) { const int q = tih + 256 * k; if (q < 1608) *(LAS v4u*)(hb + RAW_OFF + q * 16) = pre[k]; }
;         __syncthreads();
;     ...
;         if (!(P.flags & 256))
;     ...
;         {
;             const int t = t1;
; #pragma unroll
;             for (int p = 0; p < 3; ++p) {
;                 float acc[16];
; #pragma unroll
;                 for (int i = 0; i < 16; ++i) acc[i] = 0.f;
; #pragma unroll
;                 for (int j = 0; j < 4; ++j) {
;                     float rw[16];
;                     { const LAS v4u* rp = (const LAS v4u*)(hb + RAW_OFF + (t + j) * 384 + (p * 64 + 16 * cg) * 2);
;                       float f0[8], f1[8]; unpack8(rp[0], f0); unpack8(rp[1], f1);
; #pragma unroll
;                       for (int i = 0; i < 8; ++i) { rw[i] = f0[i]; rw[8 + i] = f1[i]; } }
;                     const LAS float* cwj = (const LAS float*)(hb + CW_OFF) + j * 192 + p * 64 + 16 * cg;
; #pragma unroll
;                     for (int i4 = 0; i4 < 4; ++i4) { const f32x4 w = ((const LAS f32x4*)cwj)[i4];
;                         acc[4 * i4] += rw[4 * i4] * w[0]; acc[4 * i4 + 1] += rw[4 * i4 + 1] * w[1]; acc[4 * i4 + 2] += rw[4 * i4 + 2] * w[2]; acc[4 * i4 + 3] += rw[4 * i4 + 3] * w[3]; }
;                 }
.LBB0_351:
	s_waitcnt vmcnt(8)
	ds_write_b128 v156, v[2:5] offset:27648
	ds_write_b128 v157, v[6:9] offset:27648
	ds_write_b128 v158, v[10:13] offset:27648
	ds_write_b128 v159, v[14:17] offset:27648
	ds_write_b128 v160, v[18:21] offset:27648
	ds_write_b128 v161, v[22:25] offset:27648
	s_and_saveexec_b64 s[14:15], s[34:35]
	ds_write_b128 v162, v[26:29] offset:27648
	s_or_b64 exec, exec, s[14:15]
	s_waitcnt lgkmcnt(0)
	s_barrier
	ds_read_b128 v[36:39], v163 offset:27648
	ds_read_b128 v[66:69], v163 offset:27664
	ds_read_b128 v[32:35], v164 offset:59648
	ds_read_b128 v[70:73], v164 offset:59664
	ds_read_b128 v[74:77], v164 offset:59680
	ds_read_b128 v[60:63], v164 offset:59696
	ds_read_b128 v[44:47], v163 offset:28032
	ds_read_b128 v[188:191], v163 offset:28048
	ds_read_b128 v[40:43], v164 offset:60416
	ds_read_b128 v[192:195], v164 offset:60432
	ds_read_b128 v[196:199], v164 offset:60448
	ds_read_b128 v[200:203], v164 offset:60464
	ds_read_b128 v[48:51], v163 offset:28416
	ds_read_b128 v[204:207], v163 offset:28432
	ds_read_b128 v[208:211], v164 offset:61216
	ds_read_b128 v[212:215], v164 offset:61232
	ds_read_b128 v[52:55], v163 offset:28800
	ds_read_b128 v[216:219], v163 offset:28816
	ds_read_b128 v[220:223], v164 offset:61984
	ds_read_b128 v[224:227], v164 offset:62000
	s_waitcnt lgkmcnt(14)
	v_lshlrev_b32_e32 v56, 16, v69
	v_and_b32_e32 v57, 0xffff0000, v69
	v_pk_fma_f32 v[56:57], v[62:63], v[56:57], 0 op_sel_hi:[1,1,0]
	s_waitcnt lgkmcnt(12)
	v_lshlrev_b32_e32 v58, 16, v191
	v_and_b32_e32 v59, 0xffff0000, v191
	s_waitcnt lgkmcnt(8)
	v_pk_fma_f32 v[56:57], v[202:203], v[58:59], v[56:57]
	s_waitcnt lgkmcnt(6)
	v_lshlrev_b32_e32 v58, 16, v207
	v_and_b32_e32 v59, 0xffff0000, v207
	v_lshlrev_b32_e32 v202, 16, v68
	v_and_b32_e32 v203, 0xffff0000, v68
	s_waitcnt lgkmcnt(4)
	v_pk_fma_f32 v[56:57], v[214:215], v[58:59], v[56:57]
	s_waitcnt lgkmcnt(2)
	v_lshlrev_b32_e32 v58, 16, v219
	v_and_b32_e32 v59, 0xffff0000, v219
	v_pk_fma_f32 v[60:61], v[60:61], v[202:203], 0 op_sel_hi:[1,1,0]
	v_lshlrev_b32_e32 v68, 16, v190
	v_and_b32_e32 v69, 0xffff0000, v190
	s_waitcnt lgkmcnt(0)
	v_pk_fma_f32 v[62:63], v[226:227], v[58:59], v[56:57]
	v_pk_fma_f32 v[60:61], v[200:201], v[68:69], v[60:61]
	v_lshlrev_b32_e32 v68, 16, v206
	v_and_b32_e32 v69, 0xffff0000, v206
	v_mul_f32_e32 v31, 0xbfb8aa3b, v62
	v_pk_fma_f32 v[60:61], v[212:213], v[68:69], v[60:61]
	v_lshlrev_b32_e32 v68, 16, v218
	v_and_b32_e32 v69, 0xffff0000, v218
	v_exp_f32_e32 v31, v31
	v_mul_f32_e32 v56, 0xbfb8aa3b, v63
	v_pk_fma_f32 v[68:69], v[224:225], v[68:69], v[60:61]
	v_exp_f32_e32 v65, v56
	v_mul_f32_e32 v60, 0xbfb8aa3b, v68
	v_exp_f32_e32 v60, v60
	v_mul_f32_e32 v61, 0xbfb8aa3b, v69
	v_exp_f32_e32 v61, v61
	v_add_f32_e32 v31, 1.0, v31
	v_rcp_f32_e32 v64, v31
	v_add_f32_e32 v31, 1.0, v65
	v_rcp_f32_e32 v65, v31
	v_add_f32_e32 v31, 1.0, v60
	v_rcp_f32_e32 v190, v31
	v_add_f32_e32 v31, 1.0, v61
	v_rcp_f32_e32 v191, v31
	v_pk_mul_f32 v[60:61], v[62:63], v[64:65]
	ds_read_b128 v[56:59], v164 offset:61184
	ds_read_b128 v[226:229], v164 offset:61200
	ds_read_b128 v[200:203], v164 offset:61952
	ds_read_b128 v[212:215], v164 offset:61968
	v_pk_mul_f32 v[62:63], v[68:69], v[190:191]
	v_lshlrev_b32_e32 v68, 16, v67
	v_and_b32_e32 v69, 0xffff0000, v67
	v_pk_fma_f32 v[68:69], v[76:77], v[68:69], 0 op_sel_hi:[1,1,0]
	v_lshlrev_b32_e32 v76, 16, v189
	v_and_b32_e32 v77, 0xffff0000, v189
	v_pk_fma_f32 v[68:69], v[198:199], v[76:77], v[68:69]
	v_lshlrev_b32_e32 v76, 16, v205
	v_and_b32_e32 v77, 0xffff0000, v205
	v_pk_fma_f32 v[68:69], v[210:211], v[76:77], v[68:69]
	v_lshlrev_b32_e32 v76, 16, v217
	v_and_b32_e32 v77, 0xffff0000, v217
	v_pk_fma_f32 v[68:69], v[222:223], v[76:77], v[68:69]
	v_lshlrev_b32_e32 v198, 16, v66
	v_mul_f32_e32 v31, 0xbfb8aa3b, v68
	v_exp_f32_e32 v31, v31
	v_mul_f32_e32 v67, 0xbfb8aa3b, v69
	v_exp_f32_e32 v67, v67
	v_and_b32_e32 v199, 0xffff0000, v66
	v_add_f32_e32 v31, 1.0, v31
	v_rcp_f32_e32 v190, v31
	v_add_f32_e32 v31, 1.0, v67
	v_pk_fma_f32 v[66:67], v[74:75], v[198:199], 0 op_sel_hi:[1,1,0]
	v_lshlrev_b32_e32 v74, 16, v188
	v_and_b32_e32 v75, 0xffff0000, v188
	v_pk_fma_f32 v[66:67], v[196:197], v[74:75], v[66:67]
	v_lshlrev_b32_e32 v74, 16, v204
	v_and_b32_e32 v75, 0xffff0000, v204
	v_lshlrev_b32_e32 v188, 16, v39
	v_and_b32_e32 v189, 0xffff0000, v39
	v_pk_fma_f32 v[66:67], v[208:209], v[74:75], v[66:67]
	v_lshlrev_b32_e32 v74, 16, v216
	v_and_b32_e32 v75, 0xffff0000, v216
	v_pk_fma_f32 v[72:73], v[72:73], v[188:189], 0 op_sel_hi:[1,1,0]
	v_lshlrev_b32_e32 v188, 16, v47
	v_and_b32_e32 v189, 0xffff0000, v47
	v_pk_fma_f32 v[66:67], v[220:221], v[74:75], v[66:67]
	v_pk_fma_f32 v[72:73], v[194:195], v[188:189], v[72:73]
	v_lshlrev_b32_e32 v188, 16, v51
	v_and_b32_e32 v189, 0xffff0000, v51
	v_rcp_f32_e32 v191, v31
	v_mul_f32_e32 v31, 0xbfb8aa3b, v66
	s_waitcnt lgkmcnt(2)
	v_pk_fma_f32 v[72:73], v[228:229], v[188:189], v[72:73]
	v_lshlrev_b32_e32 v188, 16, v55
	v_and_b32_e32 v189, 0xffff0000, v55
	v_exp_f32_e32 v31, v31
	v_mul_f32_e32 v74, 0xbfb8aa3b, v67
	s_waitcnt lgkmcnt(0)
; #define LAS __attribute__((address_space(3)))
; __device__ __forceinline__ unsigned pk2(float lo, float hi) { return pg8::cvt_pk_bf16_v(lo, hi); }
; __device__ __forceinline__ float siluf(float x) { return x * __builtin_amdgcn_rcpf(1.0f + __expf(-x)); }
; __device__ __forceinline__ void gdn_prep_all(const Params& P, LAS unsigned char* lds, int tid, int lane, int wave, int G) {
;     ...
;             for (int p = 0; p < 3; ++p) {
;                 float acc[16];
; #pragma unroll
;                 for (int i = 0; i < 16; ++i) acc[i] = 0.f;
; #pragma unroll
;                 for (int j = 0; j < 4; ++j) {
;                     float rw[16];
;                     { const LAS v4u* rp = (const LAS v4u*)(hb + RAW_OFF + (t + j) * 384 + (p * 64 + 16 * cg) * 2);
;                       float f0[8], f1[8]; unpack8(rp[0], f0); unpack8(rp[1], f1);
; #pragma unroll
;                       for (int i = 0; i < 8; ++i) { rw[i] = f0[i]; rw[8 + i] = f1[i]; } }
;                     const LAS float* cwj = (const LAS float*)(hb + CW_OFF) + j * 192 + p * 64 + 16 * cg;
; #pragma unroll
;                     for (int i4 = 0; i4 < 4; ++i4) { const f32x4 w = ((const LAS f32x4*)cwj)[i4];
;                         acc[4 * i4] += rw[4 * i4] * w[0]; acc[4 * i4 + 1] += rw[4 * i4 + 1] * w[1]; acc[4 * i4 + 2] += rw[4 * i4 + 2] * w[2]; acc[4 * i4 + 3] += rw[4 * i4 + 3] * w[3]; }
;                 }
;                 float ss = 0.f;
; #pragma unroll
;                 for (int i = 0; i < 16; ++i) { acc[i] = siluf(acc[i]); ss += acc[i] * acc[i]; }
;                 ss += __shfl_xor(ss, 1); ss += __shfl_xor(ss, 2);
;                 float scale = 1.f;
;                 if (p == 0) scale = 0.125f * __builtin_amdgcn_rsqf(ss + 1e-6f); else if (p == 1) scale = __builtin_amdgcn_rsqf(ss + 1e-6f);
;                 if (t >= I.L) scale = 0.f;
;                 v4u o0, o1;
;                 o0.x = pk2(acc[0] * scale, acc[1] * scale); o0.y = pk2(acc[2] * scale, acc[3] * scale); o0.z = pk2(acc[4] * scale, acc[5] * scale); o0.w = pk2(acc[6] * scale, acc[7] * scale);
;                 o1.x = pk2(acc[8] * scale, acc[9] * scale); o1.y = pk2(acc[10] * scale, acc[11] * scale); o1.z = pk2(acc[12] * scale, acc[13] * scale); o1.w = pk2(acc[14] * scale, acc[15] * scale);
;                 LAS v4u* dst = (LAS v4u*)(hb + p * 9216 + t * 144 + cg * 32);
;                 dst[0] = o0; dst[1] = o1;
	v_pk_fma_f32 v[72:73], v[214:215], v[188:189], v[72:73]
	v_exp_f32_e32 v75, v74
	v_mul_f32_e32 v39, 0xbfb8aa3b, v72
	v_exp_f32_e32 v39, v39
	v_mul_f32_e32 v47, 0xbfb8aa3b, v73
	v_exp_f32_e32 v47, v47
	v_add_f32_e32 v31, 1.0, v31
	v_rcp_f32_e32 v74, v31
	v_add_f32_e32 v31, 1.0, v75
	v_rcp_f32_e32 v75, v31
	v_add_f32_e32 v31, 1.0, v39
	v_rcp_f32_e32 v188, v31
	v_add_f32_e32 v31, 1.0, v47
	v_rcp_f32_e32 v189, v31
	v_and_b32_e32 v47, 0xffff0000, v50
	v_and_b32_e32 v55, 0xffff0000, v37
	v_pk_mul_f32 v[66:67], v[66:67], v[74:75]
	v_pk_mul_f32 v[72:73], v[72:73], v[188:189]
	v_lshlrev_b32_e32 v188, 16, v38
	v_and_b32_e32 v189, 0xffff0000, v38
	v_pk_fma_f32 v[38:39], v[70:71], v[188:189], 0 op_sel_hi:[1,1,0]
	v_lshlrev_b32_e32 v70, 16, v46
	v_and_b32_e32 v71, 0xffff0000, v46
	v_pk_fma_f32 v[38:39], v[192:193], v[70:71], v[38:39]
	v_lshlrev_b32_e32 v46, 16, v50
	v_pk_fma_f32 v[38:39], v[226:227], v[46:47], v[38:39]
	v_lshlrev_b32_e32 v46, 16, v54
	v_and_b32_e32 v47, 0xffff0000, v54
	v_pk_fma_f32 v[38:39], v[212:213], v[46:47], v[38:39]
	v_lshlrev_b32_e32 v54, 16, v37
	v_mul_f32_e32 v31, 0xbfb8aa3b, v38
	v_exp_f32_e32 v31, v31
	v_mul_f32_e32 v46, 0xbfb8aa3b, v39
	v_exp_f32_e32 v51, v46
	v_pk_fma_f32 v[34:35], v[34:35], v[54:55], 0 op_sel_hi:[1,1,0]
	v_lshlrev_b32_e32 v54, 16, v45
	v_and_b32_e32 v55, 0xffff0000, v45
	v_pk_fma_f32 v[34:35], v[42:43], v[54:55], v[34:35]
	v_lshlrev_b32_e32 v42, 16, v49
	v_and_b32_e32 v43, 0xffff0000, v49
	v_add_f32_e32 v31, 1.0, v31
	v_pk_fma_f32 v[34:35], v[58:59], v[42:43], v[34:35]
	v_lshlrev_b32_e32 v42, 16, v53
	v_and_b32_e32 v43, 0xffff0000, v53
	v_rcp_f32_e32 v50, v31
	v_add_f32_e32 v31, 1.0, v51
	v_pk_fma_f32 v[34:35], v[202:203], v[42:43], v[34:35]
	v_rcp_f32_e32 v51, v31
	v_mul_f32_e32 v31, 0xbfb8aa3b, v34
	v_exp_f32_e32 v31, v31
	v_mul_f32_e32 v37, 0xbfb8aa3b, v35
	v_exp_f32_e32 v37, v37
	v_pk_mul_f32 v[38:39], v[38:39], v[50:51]
	v_add_f32_e32 v31, 1.0, v31
	v_lshlrev_b32_e32 v50, 16, v36
	v_and_b32_e32 v51, 0xffff0000, v36
	v_rcp_f32_e32 v42, v31
	v_add_f32_e32 v31, 1.0, v37
	v_pk_fma_f32 v[32:33], v[32:33], v[50:51], 0 op_sel_hi:[1,1,0]
	v_lshlrev_b32_e32 v36, 16, v44
	v_and_b32_e32 v37, 0xffff0000, v44
	v_pk_fma_f32 v[32:33], v[40:41], v[36:37], v[32:33]
	v_lshlrev_b32_e32 v36, 16, v48
	v_and_b32_e32 v37, 0xffff0000, v48
	v_pk_fma_f32 v[32:33], v[56:57], v[36:37], v[32:33]
	v_lshlrev_b32_e32 v36, 16, v52
	v_and_b32_e32 v37, 0xffff0000, v52
	v_pk_fma_f32 v[32:33], v[200:201], v[36:37], v[32:33]
	v_rcp_f32_e32 v43, v31
	v_mul_f32_e32 v36, 0xbfb8aa3b, v32
	v_exp_f32_e32 v36, v36
	v_mul_f32_e32 v37, 0xbfb8aa3b, v33
	v_exp_f32_e32 v37, v37
	v_pk_mul_f32 v[34:35], v[34:35], v[42:43]
	v_add_f32_e32 v31, 1.0, v36
	v_rcp_f32_e32 v36, v31
	v_add_f32_e32 v31, 1.0, v37
	v_rcp_f32_e32 v37, v31
	v_pk_mul_f32 v[42:43], v[34:35], v[34:35]
	v_pk_mul_f32 v[40:41], v[38:39], v[38:39]
	v_pk_mul_f32 v[46:47], v[72:73], v[72:73]
	v_pk_mul_f32 v[32:33], v[32:33], v[36:37]
	v_pk_mul_f32 v[74:75], v[66:67], v[66:67]
	v_pk_mul_f32 v[36:37], v[32:33], v[32:33]
	v_pk_mul_f32 v[68:69], v[68:69], v[190:191]
	v_add_f32_e32 v31, v36, v37
	v_add_f32_e32 v31, v42, v31
	v_add_f32_e32 v31, v43, v31
	v_add_f32_e32 v31, v40, v31
	v_add_f32_e32 v31, v41, v31
	v_add_f32_e32 v31, v46, v31
	v_add_f32_e32 v31, v47, v31
	v_add_f32_e32 v31, v74, v31
	v_pk_mul_f32 v[190:191], v[68:69], v[68:69]
	v_add_f32_e32 v31, v75, v31
	v_add_f32_e32 v31, v190, v31
	v_pk_mul_f32 v[76:77], v[62:63], v[62:63]
	v_add_f32_e32 v31, v191, v31
	v_add_f32_e32 v31, v76, v31
	v_pk_mul_f32 v[64:65], v[60:61], v[60:61]
	v_add_f32_e32 v31, v77, v31
	v_add_f32_e32 v31, v64, v31
	v_add_f32_e32 v31, v65, v31
	ds_bpermute_b32 v36, v140, v31
	s_ashr_i32 s16, s2, 2
	s_cmpk_gt_i32 s16, 0x3ff
	s_cselect_b32 s12, 16, 64
	v_cmp_gt_u32_e32 vcc, s12, v109
	s_waitcnt lgkmcnt(0)
	v_add_f32_e32 v31, v31, v36
	ds_bpermute_b32 v36, v141, v31
	s_add_i32 s2, s2, s3
	s_cmpk_lt_i32 s2, 0x1040
	s_cselect_b64 s[92:93], -1, 0
	s_cmpk_gt_i32 s2, 0x103f
	s_waitcnt lgkmcnt(0)
	v_add_f32_e32 v31, v31, v36
	v_add_f32_e32 v31, 0x358637bd, v31
	v_rsq_f32_e32 v31, v31
	s_cselect_b64 s[90:91], -1, 0
	v_mul_f32_e32 v31, 0x3e000000, v31
	v_cndmask_b32_e32 v40, 0, v31, vcc
	v_pk_mul_f32 v[32:33], v[32:33], v[40:41] op_sel_hi:[1,0]
	v_pk_mul_f32 v[34:35], v[34:35], v[40:41] op_sel_hi:[1,0]
	v_cvt_pk_bf16_f32 v32, v32, v33
	v_cvt_pk_bf16_f32 v33, v34, v35
	v_pk_mul_f32 v[34:35], v[38:39], v[40:41] op_sel_hi:[1,0]
	v_pk_mul_f32 v[36:37], v[72:73], v[40:41] op_sel_hi:[1,0]
	v_cvt_pk_bf16_f32 v34, v34, v35
	v_cvt_pk_bf16_f32 v35, v36, v37
	v_pk_mul_f32 v[36:37], v[66:67], v[40:41] op_sel_hi:[1,0]
	v_pk_mul_f32 v[38:39], v[68:69], v[40:41] op_sel_hi:[1,0]
	v_cvt_pk_bf16_f32 v36, v36, v37
	v_cvt_pk_bf16_f32 v37, v38, v39
	v_pk_mul_f32 v[38:39], v[62:63], v[40:41] op_sel_hi:[1,0]
	v_pk_mul_f32 v[40:41], v[60:61], v[40:41] op_sel_hi:[1,0]
	v_cvt_pk_bf16_f32 v38, v38, v39
	v_cvt_pk_bf16_f32 v39, v40, v41
	ds_write_b128 v165, v[32:35]
	ds_write_b128 v165, v[36:39] offset:16
	ds_read_b128 v[36:39], v163 offset:27776
	ds_read_b128 v[66:69], v163 offset:27792
	ds_read_b128 v[32:35], v164 offset:59904
	ds_read_b128 v[70:73], v164 offset:59920
	ds_read_b128 v[74:77], v164 offset:59936
	ds_read_b128 v[60:63], v164 offset:59952
	ds_read_b128 v[44:47], v163 offset:28160
	ds_read_b128 v[188:191], v163 offset:28176
	ds_read_b128 v[40:43], v164 offset:60672
	ds_read_b128 v[192:195], v164 offset:60688
	ds_read_b128 v[196:199], v164 offset:60704
	ds_read_b128 v[200:203], v164 offset:60720
	ds_read_b128 v[48:51], v163 offset:28544
	ds_read_b128 v[204:207], v163 offset:28560
	ds_read_b128 v[208:211], v164 offset:61472
	ds_read_b128 v[212:215], v164 offset:61488
	ds_read_b128 v[52:55], v163 offset:28928
	ds_read_b128 v[216:219], v163 offset:28944
	ds_read_b128 v[220:223], v164 offset:62240
	ds_read_b128 v[224:227], v164 offset:62256
	s_waitcnt lgkmcnt(14)
; #define LAS __attribute__((address_space(3)))
; __device__ __forceinline__ float siluf(float x) { return x * __builtin_amdgcn_rcpf(1.0f + __expf(-x)); }
; __device__ __forceinline__ void unpack8(v4u w, float (&f)[8]) { f[0] = bflo(w.x); f[1] = bfhi(w.x); f[2] = bflo(w.y); f[3] = bfhi(w.y); f[4] = bflo(w.z); f[5] = bfhi(w.z); f[6] = bflo(w.w); f[7] = bfhi(w.w); }
; __device__ __forceinline__ void gdn_prep_all(const Params& P, LAS unsigned char* lds, int tid, int lane, int wave, int G) {
;     ...
;                 for (int j = 0; j < 4; ++j) {
;                     float rw[16];
;                     { const LAS v4u* rp = (const LAS v4u*)(hb + RAW_OFF + (t + j) * 384 + (p * 64 + 16 * cg) * 2);
;                       float f0[8], f1[8]; unpack8(rp[0], f0); unpack8(rp[1], f1);
; #pragma unroll
;                       for (int i = 0; i < 8; ++i) { rw[i] = f0[i]; rw[8 + i] = f1[i]; } }
;                     const LAS float* cwj = (const LAS float*)(hb + CW_OFF) + j * 192 + p * 64 + 16 * cg;
; #pragma unroll
;                     for (int i4 = 0; i4 < 4; ++i4) { const f32x4 w = ((const LAS f32x4*)cwj)[i4];
;                         acc[4 * i4] += rw[4 * i4] * w[0]; acc[4 * i4 + 1] += rw[4 * i4 + 1] * w[1]; acc[4 * i4 + 2] += rw[4 * i4 + 2] * w[2]; acc[4 * i4 + 3] += rw[4 * i4 + 3] * w[3]; }
;                 }
;                 float ss = 0.f;
; #pragma unroll
;                 for (int i = 0; i < 16; ++i) { acc[i] = siluf(acc[i]); ss += acc[i] * acc[i]; }
	v_lshlrev_b32_e32 v56, 16, v69
	v_and_b32_e32 v57, 0xffff0000, v69
	v_pk_fma_f32 v[56:57], v[62:63], v[56:57], 0 op_sel_hi:[1,1,0]
	s_waitcnt lgkmcnt(12)
	v_lshlrev_b32_e32 v58, 16, v191
	v_and_b32_e32 v59, 0xffff0000, v191
	s_waitcnt lgkmcnt(8)
	v_pk_fma_f32 v[56:57], v[202:203], v[58:59], v[56:57]
	s_waitcnt lgkmcnt(6)
	v_lshlrev_b32_e32 v58, 16, v207
	v_and_b32_e32 v59, 0xffff0000, v207
	v_lshlrev_b32_e32 v202, 16, v68
	v_and_b32_e32 v203, 0xffff0000, v68
	s_waitcnt lgkmcnt(4)
	v_pk_fma_f32 v[56:57], v[214:215], v[58:59], v[56:57]
	s_waitcnt lgkmcnt(2)
	v_lshlrev_b32_e32 v58, 16, v219
	v_and_b32_e32 v59, 0xffff0000, v219
	v_pk_fma_f32 v[60:61], v[60:61], v[202:203], 0 op_sel_hi:[1,1,0]
	v_lshlrev_b32_e32 v68, 16, v190
	v_and_b32_e32 v69, 0xffff0000, v190
	s_waitcnt lgkmcnt(0)
	v_pk_fma_f32 v[62:63], v[226:227], v[58:59], v[56:57]
	v_pk_fma_f32 v[60:61], v[200:201], v[68:69], v[60:61]
	v_lshlrev_b32_e32 v68, 16, v206
	v_and_b32_e32 v69, 0xffff0000, v206
	v_mul_f32_e32 v31, 0xbfb8aa3b, v62
	v_pk_fma_f32 v[60:61], v[212:213], v[68:69], v[60:61]
	v_lshlrev_b32_e32 v68, 16, v218
	v_and_b32_e32 v69, 0xffff0000, v218
	v_exp_f32_e32 v31, v31
	v_mul_f32_e32 v56, 0xbfb8aa3b, v63
	v_pk_fma_f32 v[68:69], v[224:225], v[68:69], v[60:61]
	v_exp_f32_e32 v65, v56
	v_mul_f32_e32 v60, 0xbfb8aa3b, v68
	v_exp_f32_e32 v60, v60
	v_mul_f32_e32 v61, 0xbfb8aa3b, v69
	v_exp_f32_e32 v61, v61
	v_add_f32_e32 v31, 1.0, v31
	v_rcp_f32_e32 v64, v31
	v_add_f32_e32 v31, 1.0, v65
	v_rcp_f32_e32 v65, v31
	v_add_f32_e32 v31, 1.0, v60
	v_rcp_f32_e32 v190, v31
	v_add_f32_e32 v31, 1.0, v61
	v_rcp_f32_e32 v191, v31
	v_pk_mul_f32 v[60:61], v[62:63], v[64:65]
	ds_read_b128 v[56:59], v164 offset:61440
	ds_read_b128 v[226:229], v164 offset:61456
	ds_read_b128 v[200:203], v164 offset:62208
	ds_read_b128 v[212:215], v164 offset:62224
	v_pk_mul_f32 v[62:63], v[68:69], v[190:191]
	v_lshlrev_b32_e32 v68, 16, v67
	v_and_b32_e32 v69, 0xffff0000, v67
	v_pk_fma_f32 v[68:69], v[76:77], v[68:69], 0 op_sel_hi:[1,1,0]
	v_lshlrev_b32_e32 v76, 16, v189
	v_and_b32_e32 v77, 0xffff0000, v189
	v_pk_fma_f32 v[68:69], v[198:199], v[76:77], v[68:69]
	v_lshlrev_b32_e32 v76, 16, v205
	v_and_b32_e32 v77, 0xffff0000, v205
	v_pk_fma_f32 v[68:69], v[210:211], v[76:77], v[68:69]
	v_lshlrev_b32_e32 v76, 16, v217
	v_and_b32_e32 v77, 0xffff0000, v217
	v_pk_fma_f32 v[68:69], v[222:223], v[76:77], v[68:69]
	v_lshlrev_b32_e32 v198, 16, v66
	v_mul_f32_e32 v31, 0xbfb8aa3b, v68
	v_exp_f32_e32 v31, v31
	v_mul_f32_e32 v67, 0xbfb8aa3b, v69
	v_exp_f32_e32 v67, v67
	v_and_b32_e32 v199, 0xffff0000, v66
	v_add_f32_e32 v31, 1.0, v31
	v_rcp_f32_e32 v190, v31
	v_add_f32_e32 v31, 1.0, v67
	v_pk_fma_f32 v[66:67], v[74:75], v[198:199], 0 op_sel_hi:[1,1,0]
	v_lshlrev_b32_e32 v74, 16, v188
	v_and_b32_e32 v75, 0xffff0000, v188
	v_pk_fma_f32 v[66:67], v[196:197], v[74:75], v[66:67]
	v_lshlrev_b32_e32 v74, 16, v204
	v_and_b32_e32 v75, 0xffff0000, v204
	v_lshlrev_b32_e32 v188, 16, v39
	v_and_b32_e32 v189, 0xffff0000, v39
	v_pk_fma_f32 v[66:67], v[208:209], v[74:75], v[66:67]
	v_lshlrev_b32_e32 v74, 16, v216
	v_and_b32_e32 v75, 0xffff0000, v216
	v_pk_fma_f32 v[72:73], v[72:73], v[188:189], 0 op_sel_hi:[1,1,0]
	v_lshlrev_b32_e32 v188, 16, v47
	v_and_b32_e32 v189, 0xffff0000, v47
	v_pk_fma_f32 v[66:67], v[220:221], v[74:75], v[66:67]
	v_pk_fma_f32 v[72:73], v[194:195], v[188:189], v[72:73]
	v_lshlrev_b32_e32 v188, 16, v51
	v_and_b32_e32 v189, 0xffff0000, v51
	v_rcp_f32_e32 v191, v31
	v_mul_f32_e32 v31, 0xbfb8aa3b, v66
	s_waitcnt lgkmcnt(2)
	v_pk_fma_f32 v[72:73], v[228:229], v[188:189], v[72:73]
	v_lshlrev_b32_e32 v188, 16, v55
	v_and_b32_e32 v189, 0xffff0000, v55
	v_exp_f32_e32 v31, v31
	v_mul_f32_e32 v74, 0xbfb8aa3b, v67
	s_waitcnt lgkmcnt(0)
	v_pk_fma_f32 v[72:73], v[214:215], v[188:189], v[72:73]
	v_exp_f32_e32 v75, v74
	v_mul_f32_e32 v39, 0xbfb8aa3b, v72
	v_exp_f32_e32 v39, v39
	v_mul_f32_e32 v47, 0xbfb8aa3b, v73
	v_exp_f32_e32 v47, v47
	v_add_f32_e32 v31, 1.0, v31
	v_rcp_f32_e32 v74, v31
	v_add_f32_e32 v31, 1.0, v75
	v_rcp_f32_e32 v75, v31
	v_add_f32_e32 v31, 1.0, v39
	v_rcp_f32_e32 v188, v31
	v_add_f32_e32 v31, 1.0, v47
	v_rcp_f32_e32 v189, v31
	v_and_b32_e32 v47, 0xffff0000, v50
	v_and_b32_e32 v55, 0xffff0000, v37
	v_pk_mul_f32 v[66:67], v[66:67], v[74:75]
	v_pk_mul_f32 v[72:73], v[72:73], v[188:189]
	v_lshlrev_b32_e32 v188, 16, v38
	v_and_b32_e32 v189, 0xffff0000, v38
	v_pk_fma_f32 v[38:39], v[70:71], v[188:189], 0 op_sel_hi:[1,1,0]
	v_lshlrev_b32_e32 v70, 16, v46
	v_and_b32_e32 v71, 0xffff0000, v46
	v_pk_fma_f32 v[38:39], v[192:193], v[70:71], v[38:39]
	v_lshlrev_b32_e32 v46, 16, v50
	v_pk_fma_f32 v[38:39], v[226:227], v[46:47], v[38:39]
	v_lshlrev_b32_e32 v46, 16, v54
	v_and_b32_e32 v47, 0xffff0000, v54
	v_pk_fma_f32 v[38:39], v[212:213], v[46:47], v[38:39]
	v_lshlrev_b32_e32 v54, 16, v37
	v_mul_f32_e32 v31, 0xbfb8aa3b, v38
	v_exp_f32_e32 v31, v31
	v_mul_f32_e32 v46, 0xbfb8aa3b, v39
	v_exp_f32_e32 v51, v46
	v_pk_fma_f32 v[34:35], v[34:35], v[54:55], 0 op_sel_hi:[1,1,0]
	v_lshlrev_b32_e32 v54, 16, v45
	v_and_b32_e32 v55, 0xffff0000, v45
	v_pk_fma_f32 v[34:35], v[42:43], v[54:55], v[34:35]
	v_lshlrev_b32_e32 v42, 16, v49
	v_and_b32_e32 v43, 0xffff0000, v49
	v_add_f32_e32 v31, 1.0, v31
	v_pk_fma_f32 v[34:35], v[58:59], v[42:43], v[34:35]
	v_lshlrev_b32_e32 v42, 16, v53
	v_and_b32_e32 v43, 0xffff0000, v53
	v_rcp_f32_e32 v50, v31
	v_add_f32_e32 v31, 1.0, v51
	v_pk_fma_f32 v[34:35], v[202:203], v[42:43], v[34:35]
	v_rcp_f32_e32 v51, v31
	v_mul_f32_e32 v31, 0xbfb8aa3b, v34
	v_exp_f32_e32 v31, v31
	v_mul_f32_e32 v37, 0xbfb8aa3b, v35
	v_exp_f32_e32 v37, v37
	v_pk_mul_f32 v[38:39], v[38:39], v[50:51]
	v_add_f32_e32 v31, 1.0, v31
; #define LAS __attribute__((address_space(3)))
; __device__ __forceinline__ unsigned pk2(float lo, float hi) { return pg8::cvt_pk_bf16_v(lo, hi); }
; __device__ __forceinline__ float siluf(float x) { return x * __builtin_amdgcn_rcpf(1.0f + __expf(-x)); }
; __device__ __forceinline__ void gdn_prep_all(const Params& P, LAS unsigned char* lds, int tid, int lane, int wave, int G) {
;     ...
;                 float ss = 0.f;
; #pragma unroll
;                 for (int i = 0; i < 16; ++i) { acc[i] = siluf(acc[i]); ss += acc[i] * acc[i]; }
;                 ss += __shfl_xor(ss, 1); ss += __shfl_xor(ss, 2);
;                 float scale = 1.f;
;                 if (p == 0) scale = 0.125f * __builtin_amdgcn_rsqf(ss + 1e-6f); else if (p == 1) scale = __builtin_amdgcn_rsqf(ss + 1e-6f);
;                 if (t >= I.L) scale = 0.f;
;                 v4u o0, o1;
;                 o0.x = pk2(acc[0] * scale, acc[1] * scale); o0.y = pk2(acc[2] * scale, acc[3] * scale); o0.z = pk2(acc[4] * scale, acc[5] * scale); o0.w = pk2(acc[6] * scale, acc[7] * scale);
;                 o1.x = pk2(acc[8] * scale, acc[9] * scale); o1.y = pk2(acc[10] * scale, acc[11] * scale); o1.z = pk2(acc[12] * scale, acc[13] * scale); o1.w = pk2(acc[14] * scale, acc[15] * scale);
;                 LAS v4u* dst = (LAS v4u*)(hb + p * 9216 + t * 144 + cg * 32);
;                 dst[0] = o0; dst[1] = o1;
	v_lshlrev_b32_e32 v50, 16, v36
	v_and_b32_e32 v51, 0xffff0000, v36
	v_rcp_f32_e32 v42, v31
	v_add_f32_e32 v31, 1.0, v37
	v_pk_fma_f32 v[32:33], v[32:33], v[50:51], 0 op_sel_hi:[1,1,0]
	v_lshlrev_b32_e32 v36, 16, v44
	v_and_b32_e32 v37, 0xffff0000, v44
	v_pk_fma_f32 v[32:33], v[40:41], v[36:37], v[32:33]
	v_lshlrev_b32_e32 v36, 16, v48
	v_and_b32_e32 v37, 0xffff0000, v48
	v_pk_fma_f32 v[32:33], v[56:57], v[36:37], v[32:33]
	v_lshlrev_b32_e32 v36, 16, v52
	v_and_b32_e32 v37, 0xffff0000, v52
	v_pk_fma_f32 v[32:33], v[200:201], v[36:37], v[32:33]
	v_rcp_f32_e32 v43, v31
	v_mul_f32_e32 v36, 0xbfb8aa3b, v32
	v_exp_f32_e32 v36, v36
	v_mul_f32_e32 v37, 0xbfb8aa3b, v33
	v_exp_f32_e32 v37, v37
	v_pk_mul_f32 v[34:35], v[34:35], v[42:43]
	v_add_f32_e32 v31, 1.0, v36
	v_rcp_f32_e32 v36, v31
	v_add_f32_e32 v31, 1.0, v37
	v_rcp_f32_e32 v37, v31
	v_pk_mul_f32 v[42:43], v[34:35], v[34:35]
	v_pk_mul_f32 v[40:41], v[38:39], v[38:39]
	v_pk_mul_f32 v[46:47], v[72:73], v[72:73]
	v_pk_mul_f32 v[32:33], v[32:33], v[36:37]
	v_pk_mul_f32 v[74:75], v[66:67], v[66:67]
	v_pk_mul_f32 v[36:37], v[32:33], v[32:33]
	v_pk_mul_f32 v[68:69], v[68:69], v[190:191]
	v_add_f32_e32 v31, v36, v37
	v_add_f32_e32 v31, v42, v31
	v_add_f32_e32 v31, v43, v31
	v_add_f32_e32 v31, v40, v31
	v_add_f32_e32 v31, v41, v31
	v_add_f32_e32 v31, v46, v31
	v_add_f32_e32 v31, v47, v31
	v_add_f32_e32 v31, v74, v31
	v_pk_mul_f32 v[190:191], v[68:69], v[68:69]
	v_add_f32_e32 v31, v75, v31
	v_add_f32_e32 v31, v190, v31
	v_pk_mul_f32 v[76:77], v[62:63], v[62:63]
	v_add_f32_e32 v31, v191, v31
	v_add_f32_e32 v31, v76, v31
	v_pk_mul_f32 v[64:65], v[60:61], v[60:61]
	v_add_f32_e32 v31, v77, v31
	v_add_f32_e32 v31, v64, v31
	v_add_f32_e32 v31, v65, v31
	ds_bpermute_b32 v36, v140, v31
	s_waitcnt lgkmcnt(0)
	v_add_f32_e32 v31, v31, v36
	ds_bpermute_b32 v36, v141, v31
	s_waitcnt lgkmcnt(0)
	v_add_f32_e32 v31, v31, v36
	v_add_f32_e32 v31, 0x358637bd, v31
	v_rsq_f32_e32 v31, v31
	s_nop 0
	v_cndmask_b32_e32 v40, 0, v31, vcc
	v_pk_mul_f32 v[32:33], v[32:33], v[40:41] op_sel_hi:[1,0]
	v_pk_mul_f32 v[34:35], v[34:35], v[40:41] op_sel_hi:[1,0]
	v_cvt_pk_bf16_f32 v32, v32, v33
	v_cvt_pk_bf16_f32 v33, v34, v35
	v_pk_mul_f32 v[34:35], v[38:39], v[40:41] op_sel_hi:[1,0]
	v_pk_mul_f32 v[36:37], v[72:73], v[40:41] op_sel_hi:[1,0]
	v_cvt_pk_bf16_f32 v34, v34, v35
	v_cvt_pk_bf16_f32 v35, v36, v37
	v_pk_mul_f32 v[36:37], v[66:67], v[40:41] op_sel_hi:[1,0]
	v_pk_mul_f32 v[38:39], v[68:69], v[40:41] op_sel_hi:[1,0]
	v_cvt_pk_bf16_f32 v36, v36, v37
	v_cvt_pk_bf16_f32 v37, v38, v39
	v_pk_mul_f32 v[38:39], v[62:63], v[40:41] op_sel_hi:[1,0]
	v_pk_mul_f32 v[40:41], v[60:61], v[40:41] op_sel_hi:[1,0]
	v_cvt_pk_bf16_f32 v38, v38, v39
	v_cvt_pk_bf16_f32 v39, v40, v41
	ds_write_b128 v165, v[32:35] offset:9216
	ds_write_b128 v165, v[36:39] offset:9232
	ds_read_b128 v[64:67], v164 offset:60160
	ds_read_b128 v[188:191], v164 offset:60176
	ds_read_b128 v[68:71], v164 offset:60192
	ds_read_b128 v[36:39], v164 offset:60208
	ds_read_b128 v[192:195], v163 offset:27904
	ds_read_b128 v[48:51], v163 offset:27920
	ds_read_b128 v[32:35], v164 offset:62512
	ds_read_b128 v[72:75], v164 offset:62496
	ds_read_b128 v[40:43], v164 offset:61744
	ds_read_b128 v[196:199], v164 offset:61728
	ds_read_b128 v[44:47], v164 offset:60976
	ds_read_b128 v[200:203], v164 offset:60960
	ds_read_b128 v[60:63], v163 offset:29072
	ds_read_b128 v[204:207], v163 offset:29056
	ds_read_b128 v[56:59], v163 offset:28688
	ds_read_b128 v[208:211], v163 offset:28672
	ds_read_b128 v[52:55], v163 offset:28304
	ds_read_b128 v[212:215], v163 offset:28288
	ds_read_b128 v[216:219], v164 offset:62480
	ds_read_b128 v[220:223], v164 offset:62464
	ds_read_b128 v[224:227], v164 offset:61712
	ds_read_b128 v[228:231], v164 offset:61696
	ds_read_b128 v[232:235], v164 offset:60944
	ds_read_b128 v[236:239], v164 offset:60928
	s_waitcnt lgkmcnt(14)
	v_lshlrev_b32_e32 v76, 16, v192
	v_and_b32_e32 v77, 0xffff0000, v192
	v_pk_fma_f32 v[64:65], v[64:65], v[76:77], 0 op_sel_hi:[1,1,0]
	s_waitcnt lgkmcnt(6)
	v_lshlrev_b32_e32 v76, 16, v212
	v_and_b32_e32 v77, 0xffff0000, v212
	s_waitcnt lgkmcnt(0)
	v_pk_fma_f32 v[64:65], v[236:237], v[76:77], v[64:65]
	v_lshlrev_b32_e32 v76, 16, v208
	v_and_b32_e32 v77, 0xffff0000, v208
	v_pk_fma_f32 v[64:65], v[228:229], v[76:77], v[64:65]
	v_lshlrev_b32_e32 v76, 16, v204
	v_and_b32_e32 v77, 0xffff0000, v204
	v_pk_fma_f32 v[64:65], v[220:221], v[76:77], v[64:65]
	v_lshlrev_b32_e32 v192, 16, v193
	v_mul_f32_e32 v31, 0xbfb8aa3b, v65
	v_exp_f32_e32 v31, v31
	v_mul_f32_e32 v76, 0xbfb8aa3b, v64
	v_and_b32_e32 v193, 0xffff0000, v193
	v_exp_f32_e32 v77, v76
	v_lshlrev_b32_e32 v212, 16, v213
	v_and_b32_e32 v213, 0xffff0000, v213
	v_pk_fma_f32 v[66:67], v[66:67], v[192:193], 0 op_sel_hi:[1,1,0]
	v_lshlrev_b32_e32 v208, 16, v209
	v_and_b32_e32 v209, 0xffff0000, v209
	v_pk_fma_f32 v[66:67], v[238:239], v[212:213], v[66:67]
	v_lshlrev_b32_e32 v204, 16, v205
	v_and_b32_e32 v205, 0xffff0000, v205
	v_pk_fma_f32 v[66:67], v[230:231], v[208:209], v[66:67]
	v_add_f32_e32 v31, 1.0, v31
	v_pk_fma_f32 v[66:67], v[222:223], v[204:205], v[66:67]
	v_rcp_f32_e32 v221, v31
	v_add_f32_e32 v31, 1.0, v77
	v_mul_f32_e32 v77, 0xbfb8aa3b, v67
	v_exp_f32_e32 v77, v77
	v_mul_f32_e32 v187, 0xbfb8aa3b, v66
	v_exp_f32_e32 v187, v187
	v_rcp_f32_e32 v220, v31
	v_add_f32_e32 v31, 1.0, v77
	v_rcp_f32_e32 v193, v31
	v_add_f32_e32 v31, 1.0, v187
	v_rcp_f32_e32 v192, v31
	v_cndmask_b32_e64 v76, 0, 1.0, vcc
	v_pk_mul_f32 v[64:65], v[64:65], v[220:221]
	v_lshlrev_b32_e32 v204, 16, v211
	v_pk_mul_f32 v[66:67], v[66:67], v[192:193]
	v_lshlrev_b32_e32 v192, 16, v194
	v_and_b32_e32 v193, 0xffff0000, v194
; #define LAS __attribute__((address_space(3)))
; __device__ __forceinline__ unsigned pk2(float lo, float hi) { return pg8::cvt_pk_bf16_v(lo, hi); }
; __device__ __forceinline__ float siluf(float x) { return x * __builtin_amdgcn_rcpf(1.0f + __expf(-x)); }
; __device__ __forceinline__ void gdn_prep_all(const Params& P, LAS unsigned char* lds, int tid, int lane, int wave, int G) {
;     ...
;                 for (int i = 0; i < 16; ++i) { acc[i] = siluf(acc[i]); ss += acc[i] * acc[i]; }
;                 ss += __shfl_xor(ss, 1); ss += __shfl_xor(ss, 2);
;                 float scale = 1.f;
;                 if (p == 0) scale = 0.125f * __builtin_amdgcn_rsqf(ss + 1e-6f); else if (p == 1) scale = __builtin_amdgcn_rsqf(ss + 1e-6f);
;                 if (t >= I.L) scale = 0.f;
;                 v4u o0, o1;
;                 o0.x = pk2(acc[0] * scale, acc[1] * scale); o0.y = pk2(acc[2] * scale, acc[3] * scale); o0.z = pk2(acc[4] * scale, acc[5] * scale); o0.w = pk2(acc[6] * scale, acc[7] * scale);
;                 o1.x = pk2(acc[8] * scale, acc[9] * scale); o1.y = pk2(acc[10] * scale, acc[11] * scale); o1.z = pk2(acc[12] * scale, acc[13] * scale); o1.w = pk2(acc[14] * scale, acc[15] * scale);
;                 LAS v4u* dst = (LAS v4u*)(hb + p * 9216 + t * 144 + cg * 32);
;                 dst[0] = o0; dst[1] = o1;
;             }
;         }
;         if (item + G < NCU * 4) GDN_PREFETCH(item + G);
	v_pk_fma_f32 v[188:189], v[188:189], v[192:193], 0 op_sel_hi:[1,1,0]
	v_lshlrev_b32_e32 v192, 16, v214
	v_and_b32_e32 v193, 0xffff0000, v214
	v_pk_fma_f32 v[188:189], v[232:233], v[192:193], v[188:189]
	v_lshlrev_b32_e32 v192, 16, v210
	v_and_b32_e32 v193, 0xffff0000, v210
	v_pk_fma_f32 v[188:189], v[224:225], v[192:193], v[188:189]
	v_lshlrev_b32_e32 v192, 16, v206
	v_and_b32_e32 v193, 0xffff0000, v206
	v_pk_fma_f32 v[188:189], v[216:217], v[192:193], v[188:189]
	v_pk_mul_f32 v[64:65], v[76:77], v[64:65] op_sel_hi:[0,1]
	v_mul_f32_e32 v31, 0xbfb8aa3b, v189
	v_lshlrev_b32_e32 v194, 16, v195
	v_and_b32_e32 v195, 0xffff0000, v195
	v_cvt_pk_bf16_f32 v64, v64, v65
	v_exp_f32_e32 v31, v31
	v_mul_f32_e32 v65, 0xbfb8aa3b, v188
	v_lshlrev_b32_e32 v192, 16, v207
	v_and_b32_e32 v193, 0xffff0000, v207
	v_lshlrev_b32_e32 v206, 16, v215
	v_and_b32_e32 v207, 0xffff0000, v215
	v_pk_fma_f32 v[190:191], v[190:191], v[194:195], 0 op_sel_hi:[1,1,0]
	v_pk_mul_f32 v[66:67], v[76:77], v[66:67] op_sel_hi:[0,1]
	v_exp_f32_e32 v77, v65
	v_and_b32_e32 v205, 0xffff0000, v211
	v_pk_fma_f32 v[190:191], v[234:235], v[206:207], v[190:191]
	v_cvt_pk_bf16_f32 v65, v66, v67
	v_pk_fma_f32 v[190:191], v[226:227], v[204:205], v[190:191]
	v_add_f32_e32 v31, 1.0, v31
	v_pk_fma_f32 v[190:191], v[218:219], v[192:193], v[190:191]
	v_rcp_f32_e32 v67, v31
	v_mul_f32_e32 v66, 0xbfb8aa3b, v191
	v_add_f32_e32 v31, 1.0, v77
	v_exp_f32_e32 v77, v66
	v_mul_f32_e32 v66, 0xbfb8aa3b, v190
	v_exp_f32_e32 v187, v66
	v_rcp_f32_e32 v66, v31
	v_add_f32_e32 v31, 1.0, v77
	v_rcp_f32_e32 v193, v31
	v_add_f32_e32 v31, 1.0, v187
	v_rcp_f32_e32 v192, v31
	v_pk_mul_f32 v[66:67], v[188:189], v[66:67]
	s_and_b64 vcc, exec, s[90:91]
	v_pk_mul_f32 v[66:67], v[76:77], v[66:67] op_sel_hi:[0,1]
	v_pk_mul_f32 v[188:189], v[190:191], v[192:193]
	v_lshlrev_b32_e32 v190, 16, v48
	v_and_b32_e32 v191, 0xffff0000, v48
	v_pk_fma_f32 v[68:69], v[68:69], v[190:191], 0 op_sel_hi:[1,1,0]
	v_lshlrev_b32_e32 v190, 16, v52
	v_and_b32_e32 v191, 0xffff0000, v52
	v_pk_fma_f32 v[68:69], v[200:201], v[190:191], v[68:69]
	v_lshlrev_b32_e32 v190, 16, v56
	v_and_b32_e32 v191, 0xffff0000, v56
	v_pk_fma_f32 v[68:69], v[196:197], v[190:191], v[68:69]
	v_lshlrev_b32_e32 v190, 16, v60
	v_and_b32_e32 v191, 0xffff0000, v60
	v_pk_fma_f32 v[68:69], v[72:73], v[190:191], v[68:69]
	v_lshlrev_b32_e32 v52, 16, v53
	v_mul_f32_e32 v31, 0xbfb8aa3b, v69
	v_exp_f32_e32 v31, v31
	v_mul_f32_e32 v48, 0xbfb8aa3b, v68
	v_exp_f32_e32 v48, v48
	v_and_b32_e32 v53, 0xffff0000, v53
	v_add_f32_e32 v31, 1.0, v31
	v_rcp_f32_e32 v73, v31
	v_add_f32_e32 v31, 1.0, v48
	v_lshlrev_b32_e32 v48, 16, v49
	v_and_b32_e32 v49, 0xffff0000, v49
	v_pk_fma_f32 v[48:49], v[70:71], v[48:49], 0 op_sel_hi:[1,1,0]
	v_lshlrev_b32_e32 v56, 16, v57
	v_and_b32_e32 v57, 0xffff0000, v57
	v_pk_fma_f32 v[48:49], v[202:203], v[52:53], v[48:49]
	v_lshlrev_b32_e32 v60, 16, v61
	v_and_b32_e32 v61, 0xffff0000, v61
	v_pk_fma_f32 v[48:49], v[198:199], v[56:57], v[48:49]
	v_rcp_f32_e32 v72, v31
	v_pk_fma_f32 v[52:53], v[74:75], v[60:61], v[48:49]
	v_pk_mul_f32 v[188:189], v[76:77], v[188:189] op_sel_hi:[0,1]
	v_mul_f32_e32 v48, 0xbfb8aa3b, v53
	v_exp_f32_e32 v48, v48
	v_mul_f32_e32 v49, 0xbfb8aa3b, v52
	v_exp_f32_e32 v49, v49
	v_cvt_pk_bf16_f32 v66, v66, v67
	v_add_f32_e32 v31, 1.0, v48
	v_rcp_f32_e32 v57, v31
	v_add_f32_e32 v31, 1.0, v49
	v_rcp_f32_e32 v56, v31
	v_pk_mul_f32 v[48:49], v[68:69], v[72:73]
	v_cvt_pk_bf16_f32 v67, v188, v189
	v_pk_mul_f32 v[48:49], v[76:77], v[48:49] op_sel_hi:[0,1]
	v_pk_mul_f32 v[52:53], v[52:53], v[56:57]
	v_lshlrev_b32_e32 v56, 16, v50
	v_and_b32_e32 v57, 0xffff0000, v50
	v_pk_fma_f32 v[36:37], v[36:37], v[56:57], 0 op_sel_hi:[1,1,0]
	v_lshlrev_b32_e32 v56, 16, v54
	v_and_b32_e32 v57, 0xffff0000, v54
	v_pk_fma_f32 v[36:37], v[44:45], v[56:57], v[36:37]
	v_lshlrev_b32_e32 v44, 16, v58
	v_and_b32_e32 v45, 0xffff0000, v58
	v_pk_fma_f32 v[36:37], v[40:41], v[44:45], v[36:37]
	v_lshlrev_b32_e32 v40, 16, v62
	v_and_b32_e32 v41, 0xffff0000, v62
	v_pk_fma_f32 v[32:33], v[32:33], v[40:41], v[36:37]
	v_pk_mul_f32 v[52:53], v[76:77], v[52:53] op_sel_hi:[0,1]
	v_mul_f32_e32 v31, 0xbfb8aa3b, v33
	v_exp_f32_e32 v31, v31
	v_mul_f32_e32 v36, 0xbfb8aa3b, v32
	v_lshlrev_b32_e32 v50, 16, v51
	v_and_b32_e32 v51, 0xffff0000, v51
	v_cvt_pk_bf16_f32 v48, v48, v49
	v_exp_f32_e32 v36, v36
	v_cvt_pk_bf16_f32 v49, v52, v53
	v_lshlrev_b32_e32 v52, 16, v55
	v_and_b32_e32 v53, 0xffff0000, v55
	v_pk_fma_f32 v[38:39], v[38:39], v[50:51], 0 op_sel_hi:[1,1,0]
	v_lshlrev_b32_e32 v44, 16, v59
	v_and_b32_e32 v45, 0xffff0000, v59
	v_pk_fma_f32 v[38:39], v[46:47], v[52:53], v[38:39]
	v_lshlrev_b32_e32 v40, 16, v63
	v_and_b32_e32 v41, 0xffff0000, v63
	v_pk_fma_f32 v[38:39], v[42:43], v[44:45], v[38:39]
	v_add_f32_e32 v31, 1.0, v31
	v_pk_fma_f32 v[34:35], v[34:35], v[40:41], v[38:39]
	v_rcp_f32_e32 v37, v31
	v_add_f32_e32 v31, 1.0, v36
	v_mul_f32_e32 v36, 0xbfb8aa3b, v35
	v_exp_f32_e32 v38, v36
	v_mul_f32_e32 v36, 0xbfb8aa3b, v34
	v_exp_f32_e32 v40, v36
	v_rcp_f32_e32 v36, v31
	v_add_f32_e32 v31, 1.0, v38
	v_rcp_f32_e32 v39, v31
	v_add_f32_e32 v31, 1.0, v40
	v_rcp_f32_e32 v38, v31
	v_pk_mul_f32 v[32:33], v[32:33], v[36:37]
	s_nop 0
	v_pk_mul_f32 v[32:33], v[76:77], v[32:33] op_sel_hi:[0,1]
	v_cvt_pk_bf16_f32 v50, v32, v33
	v_pk_mul_f32 v[32:33], v[34:35], v[38:39]
	s_nop 0
	v_pk_mul_f32 v[32:33], v[76:77], v[32:33] op_sel_hi:[0,1]
	v_cvt_pk_bf16_f32 v51, v32, v33
	ds_write_b128 v165, v[64:67] offset:18432
	ds_write_b128 v165, v[48:51] offset:18448
	s_cbranch_vccnz .LBB0_381
	s_ashr_i32 s51, s2, 2
	s_cmpk_gt_i32 s51, 0x3ff
	s_cselect_b64 s[58:59], -1, 0
	s_min_i32 s12, s51, 0x400
	s_and_b32 s61, s12, 0x7f
	s_cmpk_lt_i32 s51, 0x400
	s_mov_b64 s[14:15], -1
	s_cbranch_scc0 .LBB0_356
	s_ashr_i32 s60, s2, 9
	s_lshl_b32 s12, s60, 13
	s_lshl_b32 s13, s61, 6
	s_or_b32 s56, s13, s12
	s_mov_b64 s[14:15], 0
